# speedup vs baseline: 1.0323x; 1.0209x over previous
; __device__ __forceinline__ unsigned cvtpk(float lo, float hi) { unsigned r; asm volatile("v_cvt_pk_bf16_f32 %0, %1, %2" : "=v"(r) : "v"(lo), "v"(hi)); return r; }
; __device__ __forceinline__ float bflo(unsigned w) { return __uint_as_float(w << 16); }
; __device__ __forceinline__ float bfhi(unsigned w) { return __uint_as_float(w & 0xffff0000u); }
; __device__ __forceinline__ float fexp(float x) { return __builtin_amdgcn_exp2f(x * 1.4426950408889634f); }
; __device__ __forceinline__ int v_st(int k, int c) { const int kk = (k & ~0xC) | ((k & 4) << 1) | ((k & 8) >> 1); return ((kk >> 3) * 4 + (c >> 5)) * 512 + ((kk & 7) * 32 + (c & 31)) * 2; }
; __device__ __forceinline__ void mlstm_item(const int tid0, const P& p, int item, char* lds) {
;     ...
;         if (tid < 128) { sb[tid] = pg0; su[tid] = pg1; scm[tid] = pg2; }
;         const float U = pU, bL = pbL;
;         const float Mlast = fmaxf(m, U);
; #pragma unroll
;         for (int i = 0; i < 4; ++i) {
;             const int piece = tid + NTHR * i, s = piece >> 4, cc = (piece & 15) * 8;
;             const u32x4 kv = pk[i], vv = pv[i];
;             const float wsv = fexp(pgu[i] - Mlast);
;             *(u32x4*)(Ks + KSWZ(s, cc * 2)) = kv;
;             u32x4 ks; ks.x = cvtpk(bflo(kv.x) * wsv, bfhi(kv.x) * wsv); ks.y = cvtpk(bflo(kv.y) * wsv, bfhi(kv.y) * wsv);
;             ks.z = cvtpk(bflo(kv.z) * wsv, bfhi(kv.z) * wsv); ks.w = cvtpk(bflo(kv.w) * wsv, bfhi(kv.w) * wsv);
;             const int so = (s >> 6) * 16384 + v_st(s & 63, cc);
;             *(u32x4*)(Kt + so) = ks; *(u32x4*)(Vt + so) = vv;
;         }
;         __syncthreads();
.LBB0_167:
	s_or_b64 exec, exec, s[8:9]
	s_waitcnt vmcnt(9)
	v_max_f32_e32 v50, v189, v189
	v_max_f32_e32 v112, v193, v193
	v_max_f32_e32 v190, v112, v50
	v_lshlrev_b32_e32 v50, 3, v196
	v_and_b32_e32 v51, 0x78, v50
	v_bfe_u32 v55, v50, 5, 2
	v_sub_f32_e32 v50, v179, v190
	v_mul_f32_e32 v50, 0x3fb8aa3b, v50
	v_lshlrev_b32_e32 v178, 1, v51
	v_and_b32_e32 v51, 0x70, v196
	v_exp_f32_e32 v53, v50
	v_xad_u32 v54, v178, v51, 0
	v_ashrrev_i32_e32 v197, 4, v196
	v_lshl_add_u32 v50, v197, 8, v54
	ds_write_b128 v50, v[114:117]
	v_lshlrev_b32_e32 v50, 16, v114
	v_and_b32_e32 v51, 0xffff0000, v114
	v_mul_f32_e32 v50, v53, v50
	v_mul_f32_e32 v51, v53, v51
	v_cvt_pk_bf16_f32 v50, v50, v51
	v_lshlrev_b32_e32 v51, 16, v115
	v_and_b32_e32 v52, 0xffff0000, v115
	v_mul_f32_e32 v51, v53, v51
	v_mul_f32_e32 v52, v53, v52
	v_cvt_pk_bf16_f32 v51, v51, v52
	v_lshlrev_b32_e32 v52, 16, v116
	v_and_b32_e32 v57, 0xffff0000, v116
	v_mul_f32_e32 v52, v53, v52
	v_mul_f32_e32 v57, v53, v57
	v_and_b32_e32 v59, 48, v197
	v_lshlrev_b32_e32 v60, 1, v197
	v_cvt_pk_bf16_f32 v52, v52, v57
	v_lshlrev_b32_e32 v57, 16, v117
	v_and_b32_e32 v58, 0xffff0000, v117
	v_and_or_b32 v59, v60, 8, v59
	v_lshrrev_b32_e32 v60, 1, v197
	v_and_b32_e32 v61, 3, v197
	v_mul_f32_e32 v57, v53, v57
	v_mul_f32_e32 v53, v53, v58
	v_lshrrev_b32_e32 v59, 1, v59
	v_and_or_b32 v60, v60, 4, v61
	v_cvt_pk_bf16_f32 v53, v57, v53
	v_lshlrev_b32_e32 v57, 4, v196
	v_or_b32_e32 v59, v59, v55
	v_lshlrev_b32_e32 v60, 6, v60
	v_and_b32_e32 v56, 48, v178
	v_and_b32_e32 v58, 0xffffc000, v57
	v_lshl_or_b32 v59, v59, 9, v60
	v_or3_b32 v58, v59, v58, v56
	v_add_u32_e32 v59, s57, v58
	ds_write_b128 v59, v[50:53]
	v_add_u32_e32 v50, 0, v58
	ds_write_b128 v50, v[118:121] offset:32768
	v_sub_f32_e32 v50, v182, v190
	v_mul_f32_e32 v50, 0x3fb8aa3b, v50
	v_add_u32_e32 v58, 0x200, v196
	v_exp_f32_e32 v53, v50
	v_ashrrev_i32_e32 v198, 4, v58
	v_lshl_add_u32 v50, v198, 8, v54
	ds_write_b128 v50, v[122:125]
	v_lshlrev_b32_e32 v50, 16, v122
	v_and_b32_e32 v51, 0xffff0000, v122
	v_mul_f32_e32 v50, v53, v50
	v_mul_f32_e32 v51, v53, v51
	v_cvt_pk_bf16_f32 v50, v50, v51
	v_lshlrev_b32_e32 v51, 16, v123
	v_and_b32_e32 v52, 0xffff0000, v123
	v_mul_f32_e32 v51, v53, v51
	v_mul_f32_e32 v52, v53, v52
	v_cvt_pk_bf16_f32 v51, v51, v52
	v_lshlrev_b32_e32 v52, 16, v124
	v_and_b32_e32 v59, 0xffff0000, v124
	v_mul_f32_e32 v52, v53, v52
	v_mul_f32_e32 v59, v53, v59
	v_cvt_pk_bf16_f32 v52, v52, v59
	v_lshlrev_b32_e32 v59, 16, v125
	v_and_b32_e32 v60, 0xffff0000, v125
	v_mul_f32_e32 v59, v53, v59
	v_mul_f32_e32 v53, v53, v60
	v_cvt_pk_bf16_f32 v53, v59, v53
	v_and_b32_e32 v59, 48, v198
	v_lshlrev_b32_e32 v60, 1, v198
	v_and_or_b32 v59, v60, 8, v59
	v_lshrrev_b32_e32 v60, 1, v198
	v_and_b32_e32 v61, 3, v198
	v_lshrrev_b32_e32 v59, 1, v59
	v_and_or_b32 v60, v60, 4, v61
	v_lshlrev_b32_e32 v58, 4, v58
	v_or_b32_e32 v59, v59, v55
	v_lshlrev_b32_e32 v60, 6, v60
	v_and_b32_e32 v58, 0xffffc000, v58
	v_lshl_or_b32 v59, v59, 9, v60
	v_or3_b32 v58, v59, v58, v56
	v_add_u32_e32 v59, s57, v58
	ds_write_b128 v59, v[50:53]
	v_add_u32_e32 v50, 0, v58
	ds_write_b128 v50, v[126:129] offset:32768
	v_sub_f32_e32 v50, v186, v190
	v_mul_f32_e32 v50, 0x3fb8aa3b, v50
	v_add_u32_e32 v58, 0x400, v196
	v_exp_f32_e32 v53, v50
	v_ashrrev_i32_e32 v199, 4, v58
	v_lshl_add_u32 v50, v199, 8, v54
	ds_write_b128 v50, v[130:133]
	v_lshlrev_b32_e32 v50, 16, v130
	v_and_b32_e32 v51, 0xffff0000, v130
	v_mul_f32_e32 v50, v53, v50
	v_mul_f32_e32 v51, v53, v51
	v_cvt_pk_bf16_f32 v50, v50, v51
	v_lshlrev_b32_e32 v51, 16, v131
	v_and_b32_e32 v52, 0xffff0000, v131
	v_mul_f32_e32 v51, v53, v51
	v_mul_f32_e32 v52, v53, v52
	v_cvt_pk_bf16_f32 v51, v51, v52
	v_lshlrev_b32_e32 v52, 16, v132
	v_and_b32_e32 v59, 0xffff0000, v132
	v_mul_f32_e32 v52, v53, v52
	v_mul_f32_e32 v59, v53, v59
	v_cvt_pk_bf16_f32 v52, v52, v59
	v_lshlrev_b32_e32 v59, 16, v133
	v_and_b32_e32 v60, 0xffff0000, v133
	v_mul_f32_e32 v59, v53, v59
	v_mul_f32_e32 v53, v53, v60
	v_cvt_pk_bf16_f32 v53, v59, v53
	v_and_b32_e32 v59, 48, v199
	v_lshlrev_b32_e32 v60, 1, v199
	v_and_or_b32 v59, v60, 8, v59
	v_lshrrev_b32_e32 v60, 1, v199
	v_and_b32_e32 v61, 3, v199
	v_lshrrev_b32_e32 v59, 1, v59
	v_and_or_b32 v60, v60, 4, v61
	v_lshlrev_b32_e32 v58, 4, v58
	v_or_b32_e32 v59, v59, v55
	v_lshlrev_b32_e32 v60, 6, v60
	v_and_b32_e32 v58, 0xffffc000, v58
	v_lshl_or_b32 v59, v59, 9, v60
	v_or3_b32 v58, v59, v58, v56
	v_add_u32_e32 v59, s57, v58
	ds_write_b128 v59, v[50:53]
	v_add_u32_e32 v50, 0, v58
	ds_write_b128 v50, v[134:137] offset:32768
	v_sub_f32_e32 v50, v187, v190
	v_mul_f32_e32 v50, 0x3fb8aa3b, v50
	v_add_u32_e32 v58, 0x600, v196
	v_exp_f32_e32 v53, v50
	v_ashrrev_i32_e32 v200, 4, v58
	v_lshl_add_u32 v50, v200, 8, v54
	ds_write_b128 v50, v[138:141]
	v_lshlrev_b32_e32 v50, 16, v138
	v_and_b32_e32 v51, 0xffff0000, v138
	v_mul_f32_e32 v50, v53, v50
	v_mul_f32_e32 v51, v53, v51
	v_cvt_pk_bf16_f32 v50, v50, v51
	v_lshlrev_b32_e32 v51, 16, v139
	v_and_b32_e32 v52, 0xffff0000, v139
	v_mul_f32_e32 v51, v53, v51
	v_mul_f32_e32 v52, v53, v52
	v_cvt_pk_bf16_f32 v51, v51, v52
	v_lshlrev_b32_e32 v52, 16, v140
	v_and_b32_e32 v54, 0xffff0000, v140
	v_mul_f32_e32 v52, v53, v52
	v_mul_f32_e32 v54, v53, v54
	v_cvt_pk_bf16_f32 v52, v52, v54
	v_lshlrev_b32_e32 v54, 16, v141
	v_and_b32_e32 v59, 0xffff0000, v141
	v_mul_f32_e32 v54, v53, v54
	v_mul_f32_e32 v53, v53, v59
	v_cvt_pk_bf16_f32 v53, v54, v53
	v_lshlrev_b32_e32 v54, 4, v58
	v_and_b32_e32 v58, 48, v200
	v_lshlrev_b32_e32 v59, 1, v200
	v_and_or_b32 v58, v59, 8, v58
	v_lshrrev_b32_e32 v58, 1, v58
	v_lshrrev_b32_e32 v59, 1, v200
	v_or_b32_e32 v55, v58, v55
	v_and_b32_e32 v58, 3, v200
	v_and_or_b32 v58, v59, 4, v58
	v_lshlrev_b32_e32 v58, 6, v58
	v_and_b32_e32 v54, 0xffffc000, v54
	v_lshl_or_b32 v55, v55, 9, v58
	v_or3_b32 v54, v55, v54, v56
	v_lshlrev_b32_e32 v113, 8, v191
	v_add_u32_e32 v55, s57, v54
	v_and_b32_e32 v194, 0x70, v57
	v_add_u32_e32 v195, s49, v113
	ds_write_b128 v55, v[50:53]
	v_add_u32_e32 v50, 0, v54
	v_xad_u32 v54, v0, v194, v195
	ds_write_b128 v50, v[142:145] offset:32768
	s_waitcnt lgkmcnt(0)
	s_barrier
; __device__ __forceinline__ float bf2f(short x) { return __uint_as_float(((unsigned)(unsigned short)x) << 16); }
; __device__ __forceinline__ void mlstm_item(const int tid0, const P& p, int item, char* lds) {
;     ...
;         f32x16 o0 = {}, o1 = {};
; #pragma unroll
;         for (int d0 = 0; d0 < 8; ++d0) { const int cb = (d0 * 16 + hi * 8) * 2;
;             const bf16x8 c0 = *reinterpret_cast<const bf16x8*>(Cs + KSWZ(64 * vh + r32, cb));
;             const bf16x8 c1 = *reinterpret_cast<const bf16x8*>(Cs + KSWZ(64 * vh + 32 + r32, cb));
;             o0 = __builtin_amdgcn_mfma_f32_32x32x16_bf16(qr[d0], c0, o0, 0, 0, 0);
;             o1 = __builtin_amdgcn_mfma_f32_32x32x16_bf16(qr[d0], c1, o1, 0, 0, 0); }
;         float nq = 0.f;
; #pragma unroll
;         for (int d0 = 0; d0 < 8; ++d0)
; #pragma unroll
;             for (int i = 0; i < 8; ++i) nq += bf2f(qr[d0][i]) * nvec[16 * d0 + 8 * hi + i];
	ds_read_b128 v[50:53], v54
	ds_read_b128 v[66:69], v54 offset:8192
	s_waitcnt vmcnt(7) lgkmcnt(1)
	v_mfma_f32_32x32x16_bf16 v[50:65], v[174:177], v[50:53], 0
	v_or_b32_e32 v180, 32, v0
	v_xad_u32 v74, v180, v194, v195
	ds_read_b128 v[70:73], v74
	ds_read_b128 v[106:109], v74 offset:8192
	v_or_b32_e32 v181, 64, v0
	v_xad_u32 v74, v181, v194, v195
	v_or_b32_e32 v211, 0x60, v0
	v_or_b32_e32 v213, 0x80, v0
	s_waitcnt vmcnt(6) lgkmcnt(1)
	v_mfma_f32_32x32x16_bf16 v[50:65], v[170:173], v[70:73], v[50:65]
	ds_read_b128 v[70:73], v74
	ds_read_b128 v[102:105], v74 offset:8192
	v_xad_u32 v74, v211, v194, v195
	v_or_b32_e32 v214, 0xa0, v0
	v_or_b32_e32 v215, 0xc0, v0
	v_or_b32_e32 v216, 0xe0, v0
	v_lshlrev_b32_e32 v192, 3, v110
	v_lshl_add_u32 v206, v201, 2, 0
	s_waitcnt vmcnt(5) lgkmcnt(1)
	v_mfma_f32_32x32x16_bf16 v[50:65], v[166:169], v[70:73], v[50:65]
	ds_read_b128 v[70:73], v74
	ds_read_b128 v[98:101], v74 offset:8192
	v_xad_u32 v74, v213, v194, v195
	v_and_b32_e32 v111, 63, v196
	v_cmp_gt_u32_e64 s[8:9], 32, v111
	v_lshl_add_u32 v207, v191, 2, s38
	s_waitcnt vmcnt(4) lgkmcnt(1)
	v_mfma_f32_32x32x16_bf16 v[50:65], v[162:165], v[70:73], v[50:65]
	ds_read_b128 v[70:73], v74
	ds_read_b128 v[94:97], v74 offset:8192
	v_xad_u32 v74, v214, v194, v195
	s_waitcnt vmcnt(3) lgkmcnt(1)
	v_mfma_f32_32x32x16_bf16 v[50:65], v[158:161], v[70:73], v[50:65]
	ds_read_b128 v[70:73], v74
	ds_read_b128 v[90:93], v74 offset:8192
	v_xad_u32 v74, v215, v194, v195
	s_waitcnt vmcnt(2) lgkmcnt(1)
	v_mfma_f32_32x32x16_bf16 v[50:65], v[154:157], v[70:73], v[50:65]
	ds_read_b128 v[70:73], v74
	ds_read_b128 v[82:85], v74 offset:8192
	v_xad_u32 v74, v216, v194, v195
	s_waitcnt vmcnt(1) lgkmcnt(1)
	v_mfma_f32_32x32x16_bf16 v[50:65], v[150:153], v[70:73], v[50:65]
	ds_read_b128 v[70:73], v74
	ds_read_b128 v[86:89], v74 offset:8192
	s_waitcnt vmcnt(0) lgkmcnt(1)
	v_mfma_f32_32x32x16_bf16 v[50:65], v[146:149], v[70:73], v[50:65]
	v_lshl_add_u32 v70, v192, 2, 0
	v_add_u32_e32 v70, 0x20600, v70
	ds_read_b128 v[72:75], v70
	ds_read_b128 v[76:79], v70 offset:16
	v_lshlrev_b32_e32 v71, 16, v174
	s_waitcnt lgkmcnt(1)
	v_fma_f32 v202, v72, v71, 0
	v_and_b32_e32 v71, 0xffff0000, v174
	v_fmac_f32_e32 v202, v73, v71
	v_lshlrev_b32_e32 v71, 16, v175
	v_fmac_f32_e32 v202, v74, v71
	v_and_b32_e32 v71, 0xffff0000, v175
	v_fmac_f32_e32 v202, v75, v71
	v_lshlrev_b32_e32 v71, 16, v176
	ds_read_b128 v[72:75], v70 offset:64
	s_waitcnt lgkmcnt(1)
	v_fmac_f32_e32 v202, v76, v71
	v_and_b32_e32 v71, 0xffff0000, v176
	v_fmac_f32_e32 v202, v77, v71
	v_lshlrev_b32_e32 v71, 16, v177
	v_fmac_f32_e32 v202, v78, v71
	v_and_b32_e32 v71, 0xffff0000, v177
	v_fmac_f32_e32 v202, v79, v71
	v_lshlrev_b32_e32 v71, 16, v170
	s_waitcnt lgkmcnt(0)
	v_fmac_f32_e32 v202, v72, v71
	v_and_b32_e32 v71, 0xffff0000, v170
	v_fmac_f32_e32 v202, v73, v71
	v_lshlrev_b32_e32 v71, 16, v171
	v_fmac_f32_e32 v202, v74, v71
	v_and_b32_e32 v71, 0xffff0000, v171
	v_fmac_f32_e32 v202, v75, v71
	ds_read_b128 v[72:75], v70 offset:80
	v_lshlrev_b32_e32 v71, 16, v172
	s_waitcnt lgkmcnt(0)
	v_fmac_f32_e32 v202, v72, v71
	v_and_b32_e32 v71, 0xffff0000, v172
	v_fmac_f32_e32 v202, v73, v71
	v_lshlrev_b32_e32 v71, 16, v173
	v_fmac_f32_e32 v202, v74, v71
	v_and_b32_e32 v71, 0xffff0000, v173
	v_fmac_f32_e32 v202, v75, v71
	ds_read_b128 v[72:75], v70 offset:128
	v_lshlrev_b32_e32 v71, 16, v166
	s_waitcnt lgkmcnt(0)
	v_fmac_f32_e32 v202, v72, v71
	v_and_b32_e32 v71, 0xffff0000, v166
	v_fmac_f32_e32 v202, v73, v71
	v_lshlrev_b32_e32 v71, 16, v167
	v_fmac_f32_e32 v202, v74, v71
	v_and_b32_e32 v71, 0xffff0000, v167
	v_fmac_f32_e32 v202, v75, v71
	ds_read_b128 v[72:75], v70 offset:144
	v_lshlrev_b32_e32 v71, 16, v168
	s_waitcnt lgkmcnt(0)
	v_fmac_f32_e32 v202, v72, v71
	v_and_b32_e32 v71, 0xffff0000, v168
	v_fmac_f32_e32 v202, v73, v71
	v_lshlrev_b32_e32 v71, 16, v169
	v_fmac_f32_e32 v202, v74, v71
	v_and_b32_e32 v71, 0xffff0000, v169
	v_fmac_f32_e32 v202, v75, v71
	ds_read_b128 v[72:75], v70 offset:192
	v_lshlrev_b32_e32 v71, 16, v162
	s_waitcnt lgkmcnt(0)
	v_fmac_f32_e32 v202, v72, v71
	v_and_b32_e32 v71, 0xffff0000, v162
	v_fmac_f32_e32 v202, v73, v71
	v_lshlrev_b32_e32 v71, 16, v163
	v_fmac_f32_e32 v202, v74, v71
	v_and_b32_e32 v71, 0xffff0000, v163
	v_fmac_f32_e32 v202, v75, v71
	ds_read_b128 v[72:75], v70 offset:208
	v_lshlrev_b32_e32 v71, 16, v164
	s_waitcnt lgkmcnt(0)
	v_fmac_f32_e32 v202, v72, v71
	v_and_b32_e32 v71, 0xffff0000, v164
	v_fmac_f32_e32 v202, v73, v71
	v_lshlrev_b32_e32 v71, 16, v165
	v_fmac_f32_e32 v202, v74, v71
	v_and_b32_e32 v71, 0xffff0000, v165
	v_fmac_f32_e32 v202, v75, v71
	ds_read_b128 v[72:75], v70 offset:256
	v_lshlrev_b32_e32 v71, 16, v158
	s_waitcnt lgkmcnt(0)
	v_fmac_f32_e32 v202, v72, v71
	v_and_b32_e32 v71, 0xffff0000, v158
	v_fmac_f32_e32 v202, v73, v71
	v_lshlrev_b32_e32 v71, 16, v159
	v_fmac_f32_e32 v202, v74, v71
	v_and_b32_e32 v71, 0xffff0000, v159
	v_fmac_f32_e32 v202, v75, v71
	ds_read_b128 v[72:75], v70 offset:272
	v_lshlrev_b32_e32 v71, 16, v160
	s_waitcnt lgkmcnt(0)
	v_fmac_f32_e32 v202, v72, v71
	v_and_b32_e32 v71, 0xffff0000, v160
	v_fmac_f32_e32 v202, v73, v71
	v_lshlrev_b32_e32 v71, 16, v161
	v_fmac_f32_e32 v202, v74, v71
	v_and_b32_e32 v71, 0xffff0000, v161
	v_fmac_f32_e32 v202, v75, v71
	ds_read_b128 v[72:75], v70 offset:320
	v_lshlrev_b32_e32 v71, 16, v154
	s_waitcnt lgkmcnt(0)
	v_fmac_f32_e32 v202, v72, v71
	v_and_b32_e32 v71, 0xffff0000, v154
	v_fmac_f32_e32 v202, v73, v71
	v_lshlrev_b32_e32 v71, 16, v155
	v_fmac_f32_e32 v202, v74, v71
	v_and_b32_e32 v71, 0xffff0000, v155
	v_fmac_f32_e32 v202, v75, v71
	ds_read_b128 v[72:75], v70 offset:336
	v_lshlrev_b32_e32 v71, 16, v156
	s_waitcnt lgkmcnt(0)
; __device__ __forceinline__ float bf2f(short x) { return __uint_as_float(((unsigned)(unsigned short)x) << 16); }
; __device__ __forceinline__ float fexp(float x) { return __builtin_amdgcn_exp2f(x * 1.4426950408889634f); }
; __device__ __forceinline__ int crow(int r, int hi) { return (r & 3) + 8 * (r >> 2) + 4 * hi; }
; __device__ __forceinline__ void mlstm_item(const int tid0, const P& p, int item, char* lds) {
;     ...
;             for (int i = 0; i < 8; ++i) nq += bf2f(qr[d0][i]) * nvec[16 * d0 + 8 * hi + i];
;         nq = xadd<32>(nq);
;         const float Mt = fmaxf(m, scm[tl]), winter = fexp(m - Mt);
;         if (hi == 0) wsr[r32] = winter;
;         asm volatile("s_waitcnt lgkmcnt(0)" ::: "memory");
; #pragma unroll
;         for (int r = 0; r < 16; ++r) { const float f = wsr[crow(r, hi)]; o0[r] *= f; o1[r] *= f; }
;         float dsum = 0.f;
;         const float MtL = Mt * 1.4426950408889634f;
; #pragma unroll
;         for (int kt = 0; kt < 2; ++kt) {
;             if (dir ? (kt == 0 && w4 >= 2) : (kt == 1 && w4 < 2)) continue;
	v_fmac_f32_e32 v202, v72, v71
	v_and_b32_e32 v71, 0xffff0000, v156
	v_fmac_f32_e32 v202, v73, v71
	v_lshlrev_b32_e32 v71, 16, v157
	v_fmac_f32_e32 v202, v74, v71
	v_and_b32_e32 v71, 0xffff0000, v157
	v_fmac_f32_e32 v202, v75, v71
	ds_read_b128 v[72:75], v70 offset:384
	v_lshlrev_b32_e32 v71, 16, v150
	s_waitcnt lgkmcnt(0)
	v_fmac_f32_e32 v202, v72, v71
	v_and_b32_e32 v71, 0xffff0000, v150
	v_fmac_f32_e32 v202, v73, v71
	v_lshlrev_b32_e32 v71, 16, v151
	v_fmac_f32_e32 v202, v74, v71
	v_and_b32_e32 v71, 0xffff0000, v151
	v_fmac_f32_e32 v202, v75, v71
	ds_read_b128 v[72:75], v70 offset:400
	v_lshlrev_b32_e32 v71, 16, v152
	s_waitcnt lgkmcnt(0)
	v_fmac_f32_e32 v202, v72, v71
	v_and_b32_e32 v71, 0xffff0000, v152
	v_fmac_f32_e32 v202, v73, v71
	v_lshlrev_b32_e32 v71, 16, v153
	v_fmac_f32_e32 v202, v74, v71
	v_and_b32_e32 v71, 0xffff0000, v153
	v_fmac_f32_e32 v202, v75, v71
	ds_read_b128 v[72:75], v70 offset:448
	v_lshlrev_b32_e32 v71, 16, v146
	s_waitcnt lgkmcnt(0)
	v_fmac_f32_e32 v202, v72, v71
	v_and_b32_e32 v71, 0xffff0000, v146
	v_fmac_f32_e32 v202, v73, v71
	v_lshlrev_b32_e32 v71, 16, v147
	v_fmac_f32_e32 v202, v74, v71
	v_and_b32_e32 v71, 0xffff0000, v147
	v_fmac_f32_e32 v202, v75, v71
	ds_read_b128 v[70:73], v70 offset:464
	v_lshlrev_b32_e32 v74, 16, v148
	s_waitcnt lgkmcnt(0)
	v_fmac_f32_e32 v202, v70, v74
	v_and_b32_e32 v70, 0xffff0000, v148
	v_fmac_f32_e32 v202, v71, v70
	v_lshlrev_b32_e32 v70, 16, v149
	v_fmac_f32_e32 v202, v72, v70
	v_and_b32_e32 v70, 0xffff0000, v149
	v_fmac_f32_e32 v202, v73, v70
	v_mfma_f32_32x32x16_bf16 v[66:81], v[174:177], v[66:69], 0
	v_mov_b32_e32 v205, v202
	s_nop 1
	v_permlane32_swap_b32_e32 v202, v205
	v_mfma_f32_32x32x16_bf16 v[66:81], v[170:173], v[106:109], v[66:81]
	v_mfma_f32_32x32x16_bf16 v[66:81], v[166:169], v[102:105], v[66:81]
	v_mfma_f32_32x32x16_bf16 v[66:81], v[162:165], v[98:101], v[66:81]
	v_mfma_f32_32x32x16_bf16 v[66:81], v[158:161], v[94:97], v[66:81]
	v_mfma_f32_32x32x16_bf16 v[66:81], v[154:157], v[90:93], v[66:81]
	v_mfma_f32_32x32x16_bf16 v[66:81], v[150:153], v[82:85], v[66:81]
	v_add_u32_e32 v82, 0x20400, v206
	ds_read_b32 v82, v82
	s_waitcnt lgkmcnt(0)
	v_max_f32_e32 v82, v82, v82
	v_mfma_f32_32x32x16_bf16 v[66:81], v[146:149], v[86:89], v[66:81]
	v_max_f32_e32 v210, v112, v82
	v_sub_f32_e32 v82, v193, v210
	v_mul_f32_e32 v82, 0x3fb8aa3b, v82
	v_exp_f32_e32 v209, v82
	s_and_saveexec_b64 s[22:23], s[8:9]
	ds_write_b32 v207, v209
	s_or_b64 exec, exec, s[22:23]
	v_lshlrev_b32_e32 v83, 4, v111
	v_lshlrev_b32_e32 v82, 3, v111
	v_and_b32_e32 v83, 0xc0, v83
	v_and_or_b32 v98, v82, 24, v83
	v_lshlrev_b32_e32 v83, 1, v111
	s_waitcnt lgkmcnt(0)
	v_add_u32_e32 v94, s38, v0
	v_and_b32_e32 v99, 32, v83
	v_and_b32_e32 v100, 0x100, v82
	ds_read_b128 v[82:85], v94 offset:64
	ds_read_b128 v[86:89], v94 offset:96
	ds_read_b128 v[90:93], v94
	ds_read_b128 v[94:97], v94 offset:32
	v_or3_b32 v204, v98, v99, v100
	s_waitcnt lgkmcnt(3)
	v_pk_mul_f32 v[58:59], v[58:59], v[82:83]
	v_pk_mul_f32 v[74:75], v[74:75], v[82:83]
	v_lshlrev_b32_e32 v82, 4, v191
	s_waitcnt lgkmcnt(2)
	v_pk_mul_f32 v[62:63], v[62:63], v[86:87]
	v_pk_mul_f32 v[64:65], v[64:65], v[88:89]
	v_pk_mul_f32 v[60:61], v[60:61], v[84:85]
	v_pk_mul_f32 v[78:79], v[78:79], v[86:87]
	v_pk_mul_f32 v[80:81], v[80:81], v[88:89]
	v_pk_mul_f32 v[76:77], v[76:77], v[84:85]
	v_bitop3_b32 v83, v0, v82, s43 bitop3:0x78
	v_bitop3_b32 v84, v180, v82, s43 bitop3:0x78
	v_bitop3_b32 v85, v181, v82, s43 bitop3:0x78
	v_bitop3_b32 v86, v211, v82, s43 bitop3:0x78
	v_bitop3_b32 v87, v213, v82, s43 bitop3:0x78
	v_bitop3_b32 v88, v214, v82, s43 bitop3:0x78
	v_bitop3_b32 v89, v215, v82, s43 bitop3:0x78
	v_bitop3_b32 v82, v216, v82, s43 bitop3:0x78
	v_add_u32_e32 v203, s56, v204
	s_waitcnt lgkmcnt(0)
	v_pk_mul_f32 v[54:55], v[54:55], v[94:95]
	v_pk_mul_f32 v[56:57], v[56:57], v[96:97]
	v_pk_mul_f32 v[52:53], v[52:53], v[92:93]
	v_pk_mul_f32 v[50:51], v[50:51], v[90:91]
	v_pk_mul_f32 v[70:71], v[70:71], v[94:95]
	v_pk_mul_f32 v[72:73], v[72:73], v[96:97]
	v_pk_mul_f32 v[68:69], v[68:69], v[92:93]
	v_pk_mul_f32 v[66:67], v[66:67], v[90:91]
	v_mul_f32_e32 v212, 0x3fb8aa3b, v210
	v_lshlrev_b32_e32 v211, 2, v110
	s_andn2_b64 vcc, exec, s[94:95]
	v_add3_u32 v220, 0, v83, v113
	v_add3_u32 v219, 0, v84, v113
	v_add3_u32 v218, 0, v85, v113
	v_add3_u32 v217, 0, v86, v113
	v_add3_u32 v216, 0, v87, v113
	v_add3_u32 v215, 0, v88, v113
	v_add3_u32 v214, 0, v89, v113
	v_add3_u32 v213, 0, v82, v113
	s_cbranch_vccnz .LBB0_235
; __device__ __forceinline__ int crow(int r, int hi) { return (r & 3) + 8 * (r >> 2) + 4 * hi; }
; __device__ __forceinline__ void mlstm_item(const int tid0, const P& p, int item, char* lds) {
;     ...
;             qkt(p0, p1, Ks + kt * 16384, qr, r32, hi);
; #pragma unroll
;             for (int r = 0; r < 16; ++r) {
;                 const int s0 = 64 * kt + crow(r, hi), s1 = s0 + 32;
;                 const bool a0 = dir ? (s0 >= tl) : (s0 <= tl), a1 = dir ? (s1 >= tl) : (s1 <= tl);
;                 const float w0 = a0 ? __builtin_amdgcn_exp2f(fminf(su[s0] * 1.4426950408889634f - MtL, 0.f)) : 0.f;
;                 const float w1 = a1 ? __builtin_amdgcn_exp2f(fminf(su[s1] * 1.4426950408889634f - MtL, 0.f)) : 0.f;
	ds_read_b128 v[82:85], v220
	ds_read_b128 v[86:89], v220 offset:8192
	ds_read_b128 v[222:225], v219
	ds_read_b128 v[226:229], v219 offset:8192
	v_cmp_le_u32_e32 vcc, v211, v201
	v_mov_b32_e32 v221, 0
	s_waitcnt lgkmcnt(3)
	v_mfma_f32_32x32x16_bf16 v[98:113], v[82:85], v[174:177], 0
	v_cndmask_b32_e64 v180, 0, 1, vcc
	v_cmp_ge_u32_e32 vcc, v211, v201
	s_nop 1
	v_cndmask_b32_e64 v181, 0, 1, vcc
	v_cndmask_b32_e64 v180, v181, v180, s[4:5]
	v_and_b32_e32 v180, 1, v180
	s_waitcnt lgkmcnt(2)
	v_mfma_f32_32x32x16_bf16 v[82:97], v[86:89], v[174:177], 0
	v_cmp_eq_u32_e32 vcc, 1, v180
	s_waitcnt lgkmcnt(1)
	v_mfma_f32_32x32x16_bf16 v[98:113], v[222:225], v[170:173], v[98:113]
	s_waitcnt lgkmcnt(0)
	v_mfma_f32_32x32x16_bf16 v[82:97], v[226:229], v[170:173], v[82:97]
	ds_read_b128 v[222:225], v218
	ds_read_b128 v[226:229], v218 offset:8192
	s_waitcnt lgkmcnt(1)
	v_mfma_f32_32x32x16_bf16 v[98:113], v[222:225], v[166:169], v[98:113]
	s_waitcnt lgkmcnt(0)
	v_mfma_f32_32x32x16_bf16 v[82:97], v[226:229], v[166:169], v[82:97]
	ds_read_b128 v[222:225], v217
	ds_read_b128 v[226:229], v217 offset:8192
	s_waitcnt lgkmcnt(1)
	v_mfma_f32_32x32x16_bf16 v[98:113], v[222:225], v[162:165], v[98:113]
	s_waitcnt lgkmcnt(0)
	v_mfma_f32_32x32x16_bf16 v[82:97], v[226:229], v[162:165], v[82:97]
	ds_read_b128 v[222:225], v216
	ds_read_b128 v[226:229], v216 offset:8192
	s_waitcnt lgkmcnt(1)
	v_mfma_f32_32x32x16_bf16 v[98:113], v[222:225], v[158:161], v[98:113]
	s_waitcnt lgkmcnt(0)
	v_mfma_f32_32x32x16_bf16 v[82:97], v[226:229], v[158:161], v[82:97]
	ds_read_b128 v[222:225], v215
	ds_read_b128 v[226:229], v215 offset:8192
	s_waitcnt lgkmcnt(1)
	v_mfma_f32_32x32x16_bf16 v[98:113], v[222:225], v[154:157], v[98:113]
	s_waitcnt lgkmcnt(0)
	v_mfma_f32_32x32x16_bf16 v[82:97], v[226:229], v[154:157], v[82:97]
	ds_read_b128 v[222:225], v214
	ds_read_b128 v[226:229], v214 offset:8192
	s_waitcnt lgkmcnt(1)
	v_mfma_f32_32x32x16_bf16 v[98:113], v[222:225], v[150:153], v[98:113]
	s_waitcnt lgkmcnt(0)
	v_mfma_f32_32x32x16_bf16 v[82:97], v[226:229], v[150:153], v[82:97]
	ds_read_b128 v[222:225], v213
	ds_read_b128 v[226:229], v213 offset:8192
	s_waitcnt lgkmcnt(1)
	v_mfma_f32_32x32x16_bf16 v[98:113], v[222:225], v[146:149], v[98:113]
	v_mov_b32_e32 v222, 0
	s_waitcnt lgkmcnt(0)
	v_mfma_f32_32x32x16_bf16 v[82:97], v[226:229], v[146:149], v[82:97]
	v_lshl_add_u32 v241, v211, 2, 0
	v_add_u32_e32 v241, 0x20200, v241
	ds_read_b32 v222, v241 offset:0
	ds_read_b32 v223, v241 offset:128
	ds_read_b32 v221, v241 offset:4
	ds_read_b32 v225, v241 offset:132
	ds_read_b32 v224, v241 offset:8
	ds_read_b32 v227, v241 offset:136
	ds_read_b32 v226, v241 offset:12
	ds_read_b32 v229, v241 offset:140
	ds_read_b32 v228, v241 offset:32
	ds_read_b32 v231, v241 offset:160
	ds_read_b32 v230, v241 offset:36
	ds_read_b32 v233, v241 offset:164
	ds_read_b32 v232, v241 offset:40
	ds_read_b32 v235, v241 offset:168
	ds_read_b32 v234, v241 offset:44
	ds_read_b32 v237, v241 offset:172
	ds_read_b32 v236, v241 offset:64
	ds_read_b32 v239, v241 offset:192
	ds_read_b32 v238, v241 offset:68
	ds_read_b32 v246, v241 offset:196
	ds_read_b32 v245, v241 offset:72
	ds_read_b32 v248, v241 offset:200
	ds_read_b32 v247, v241 offset:76
	ds_read_b32 v250, v241 offset:204
	ds_read_b32 v249, v241 offset:96
	ds_read_b32 v252, v241 offset:224
	ds_read_b32 v251, v241 offset:100
	ds_read_b32 v243, v241 offset:228
	ds_read_b32 v253, v241 offset:104
	ds_read_b32 v240, v241 offset:232
	ds_read_b32 v180, v241 offset:108
	ds_read_b32 v181, v241 offset:236
	v_sub_u32_e32 v179, v201, v211
	s_waitcnt lgkmcnt(0)
	s_cmp_lg_u64 s[4:5], 0
	s_cbranch_scc0 .Lmlw_d1_k0
	v_fma_f32 v222, v222, s41, -v212
	v_min_f32_e32 v222, 0, v222
	v_exp_f32_e32 v222, v222
	v_cmp_le_i32_e32 vcc, 0, v179
	v_fma_f32 v223, v223, s41, -v212
	v_min_f32_e32 v223, 0, v223
	v_exp_f32_e32 v223, v223
	v_cmp_le_i32_e64 s[22:23], 32, v179
	v_cndmask_b32_e32 v222, 0, v222, vcc
	v_fma_f32 v221, v221, s41, -v212
	v_min_f32_e32 v221, 0, v221
	v_exp_f32_e32 v221, v221
	v_cmp_le_i32_e32 vcc, 1, v179
	v_cndmask_b32_e64 v223, 0, v223, s[22:23]
	v_fma_f32 v225, v225, s41, -v212
	v_min_f32_e32 v225, 0, v225
	v_exp_f32_e32 v225, v225
	v_cmp_le_i32_e64 s[22:23], 33, v179
	v_cndmask_b32_e32 v221, 0, v221, vcc
	v_fma_f32 v224, v224, s41, -v212
	v_min_f32_e32 v224, 0, v224
	v_exp_f32_e32 v224, v224
	v_cmp_le_i32_e32 vcc, 2, v179
	v_cndmask_b32_e64 v225, 0, v225, s[22:23]
	v_fma_f32 v227, v227, s41, -v212
	v_min_f32_e32 v227, 0, v227
	v_exp_f32_e32 v227, v227
	v_cmp_le_i32_e64 s[22:23], 34, v179
	v_cndmask_b32_e32 v224, 0, v224, vcc
	v_fma_f32 v226, v226, s41, -v212
	v_min_f32_e32 v226, 0, v226
	v_exp_f32_e32 v226, v226
	v_cmp_le_i32_e32 vcc, 3, v179
	v_cndmask_b32_e64 v227, 0, v227, s[22:23]
	v_fma_f32 v229, v229, s41, -v212
	v_min_f32_e32 v229, 0, v229
	v_exp_f32_e32 v229, v229
	v_cmp_le_i32_e64 s[22:23], 35, v179
	v_cndmask_b32_e32 v226, 0, v226, vcc
	v_fma_f32 v228, v228, s41, -v212
	v_min_f32_e32 v228, 0, v228
	v_exp_f32_e32 v228, v228
	v_cmp_le_i32_e32 vcc, 8, v179
	v_cndmask_b32_e64 v229, 0, v229, s[22:23]
	v_fma_f32 v231, v231, s41, -v212
	v_min_f32_e32 v231, 0, v231
	v_exp_f32_e32 v231, v231
	v_cmp_le_i32_e64 s[22:23], 40, v179
	v_cndmask_b32_e32 v228, 0, v228, vcc
	v_fma_f32 v230, v230, s41, -v212
	v_min_f32_e32 v230, 0, v230
	v_exp_f32_e32 v230, v230
	v_cmp_le_i32_e32 vcc, 9, v179
	v_cndmask_b32_e64 v231, 0, v231, s[22:23]
	v_fma_f32 v233, v233, s41, -v212
	v_min_f32_e32 v233, 0, v233
	v_exp_f32_e32 v233, v233
	v_cmp_le_i32_e64 s[22:23], 41, v179
	v_cndmask_b32_e32 v230, 0, v230, vcc
	v_fma_f32 v232, v232, s41, -v212
	v_min_f32_e32 v232, 0, v232
	v_exp_f32_e32 v232, v232
; __device__ __forceinline__ int crow(int r, int hi) { return (r & 3) + 8 * (r >> 2) + 4 * hi; }
; __device__ __forceinline__ void mlstm_item(const int tid0, const P& p, int item, char* lds) {
;     ...
;             for (int r = 0; r < 16; ++r) {
;                 const int s0 = 64 * kt + crow(r, hi), s1 = s0 + 32;
;                 const bool a0 = dir ? (s0 >= tl) : (s0 <= tl), a1 = dir ? (s1 >= tl) : (s1 <= tl);
;                 const float w0 = a0 ? __builtin_amdgcn_exp2f(fminf(su[s0] * 1.4426950408889634f - MtL, 0.f)) : 0.f;
;                 const float w1 = a1 ? __builtin_amdgcn_exp2f(fminf(su[s1] * 1.4426950408889634f - MtL, 0.f)) : 0.f;
;                 p0[r] *= w0; p1[r] *= w1; dsum += p0[r] + p1[r];
	v_cmp_le_i32_e32 vcc, 10, v179
	v_cndmask_b32_e64 v233, 0, v233, s[22:23]
	v_fma_f32 v235, v235, s41, -v212
	v_min_f32_e32 v235, 0, v235
	v_exp_f32_e32 v235, v235
	v_cmp_le_i32_e64 s[22:23], 42, v179
	v_cndmask_b32_e32 v232, 0, v232, vcc
	v_fma_f32 v234, v234, s41, -v212
	v_min_f32_e32 v234, 0, v234
	v_exp_f32_e32 v234, v234
	v_cmp_le_i32_e32 vcc, 11, v179
	v_cndmask_b32_e64 v235, 0, v235, s[22:23]
	v_fma_f32 v237, v237, s41, -v212
	v_min_f32_e32 v237, 0, v237
	v_exp_f32_e32 v237, v237
	v_cmp_le_i32_e64 s[22:23], 43, v179
	v_cndmask_b32_e32 v234, 0, v234, vcc
	v_fma_f32 v236, v236, s41, -v212
	v_min_f32_e32 v236, 0, v236
	v_exp_f32_e32 v236, v236
	v_cmp_le_i32_e32 vcc, 16, v179
	v_cndmask_b32_e64 v237, 0, v237, s[22:23]
	v_fma_f32 v239, v239, s41, -v212
	v_min_f32_e32 v239, 0, v239
	v_exp_f32_e32 v239, v239
	v_cmp_le_i32_e64 s[22:23], 48, v179
	v_cndmask_b32_e32 v236, 0, v236, vcc
	v_fma_f32 v238, v238, s41, -v212
	v_min_f32_e32 v238, 0, v238
	v_exp_f32_e32 v238, v238
	v_cmp_le_i32_e32 vcc, 17, v179
	v_cndmask_b32_e64 v239, 0, v239, s[22:23]
	v_fma_f32 v246, v246, s41, -v212
	v_min_f32_e32 v246, 0, v246
	v_exp_f32_e32 v246, v246
	v_cmp_le_i32_e64 s[22:23], 49, v179
	v_cndmask_b32_e32 v238, 0, v238, vcc
	v_fma_f32 v245, v245, s41, -v212
	v_min_f32_e32 v245, 0, v245
	v_exp_f32_e32 v245, v245
	v_cmp_le_i32_e32 vcc, 18, v179
	v_cndmask_b32_e64 v246, 0, v246, s[22:23]
	v_fma_f32 v248, v248, s41, -v212
	v_min_f32_e32 v248, 0, v248
	v_exp_f32_e32 v248, v248
	v_cmp_le_i32_e64 s[22:23], 50, v179
	v_cndmask_b32_e32 v245, 0, v245, vcc
	v_fma_f32 v247, v247, s41, -v212
	v_min_f32_e32 v247, 0, v247
	v_exp_f32_e32 v247, v247
	v_cmp_le_i32_e32 vcc, 19, v179
	v_cndmask_b32_e64 v248, 0, v248, s[22:23]
	v_fma_f32 v250, v250, s41, -v212
	v_min_f32_e32 v250, 0, v250
	v_exp_f32_e32 v250, v250
	v_cmp_le_i32_e64 s[22:23], 51, v179
	v_cndmask_b32_e32 v247, 0, v247, vcc
	v_fma_f32 v249, v249, s41, -v212
	v_min_f32_e32 v249, 0, v249
	v_exp_f32_e32 v249, v249
	v_cmp_le_i32_e32 vcc, 24, v179
	v_cndmask_b32_e64 v250, 0, v250, s[22:23]
	v_fma_f32 v252, v252, s41, -v212
	v_min_f32_e32 v252, 0, v252
	v_exp_f32_e32 v252, v252
	v_cmp_le_i32_e64 s[22:23], 56, v179
	v_cndmask_b32_e32 v249, 0, v249, vcc
	v_fma_f32 v251, v251, s41, -v212
	v_min_f32_e32 v251, 0, v251
	v_exp_f32_e32 v251, v251
	v_cmp_le_i32_e32 vcc, 25, v179
	v_cndmask_b32_e64 v252, 0, v252, s[22:23]
	v_fma_f32 v243, v243, s41, -v212
	v_min_f32_e32 v243, 0, v243
	v_exp_f32_e32 v243, v243
	v_cmp_le_i32_e64 s[22:23], 57, v179
	v_cndmask_b32_e32 v251, 0, v251, vcc
	v_fma_f32 v253, v253, s41, -v212
	v_min_f32_e32 v253, 0, v253
	v_exp_f32_e32 v253, v253
	v_cmp_le_i32_e32 vcc, 26, v179
	v_cndmask_b32_e64 v243, 0, v243, s[22:23]
	v_fma_f32 v240, v240, s41, -v212
	v_min_f32_e32 v240, 0, v240
	v_exp_f32_e32 v240, v240
	v_cmp_le_i32_e64 s[22:23], 58, v179
	v_cndmask_b32_e32 v253, 0, v253, vcc
	v_fma_f32 v180, v180, s41, -v212
	v_min_f32_e32 v180, 0, v180
	v_exp_f32_e32 v180, v180
	v_cmp_le_i32_e32 vcc, 27, v179
	v_cndmask_b32_e64 v240, 0, v240, s[22:23]
	v_fma_f32 v181, v181, s41, -v212
	v_min_f32_e32 v181, 0, v181
	v_exp_f32_e32 v181, v181
	v_cmp_le_i32_e64 s[22:23], 59, v179
	v_cndmask_b32_e32 v180, 0, v180, vcc
	s_nop 1
	v_cndmask_b32_e64 v181, 0, v181, s[22:23]
	s_branch .Lmlw_done_k0
.Lmlw_d1_k0:
	v_fma_f32 v222, v222, s41, -v212
	v_min_f32_e32 v222, 0, v222
	v_exp_f32_e32 v222, v222
	v_cmp_ge_i32_e32 vcc, 0, v179
	v_fma_f32 v223, v223, s41, -v212
	v_min_f32_e32 v223, 0, v223
	v_exp_f32_e32 v223, v223
	v_cmp_ge_i32_e64 s[22:23], 32, v179
	v_cndmask_b32_e32 v222, 0, v222, vcc
	v_fma_f32 v221, v221, s41, -v212
	v_min_f32_e32 v221, 0, v221
	v_exp_f32_e32 v221, v221
	v_cmp_ge_i32_e32 vcc, 1, v179
	v_cndmask_b32_e64 v223, 0, v223, s[22:23]
	v_fma_f32 v225, v225, s41, -v212
	v_min_f32_e32 v225, 0, v225
	v_exp_f32_e32 v225, v225
	v_cmp_ge_i32_e64 s[22:23], 33, v179
	v_cndmask_b32_e32 v221, 0, v221, vcc
	v_fma_f32 v224, v224, s41, -v212
	v_min_f32_e32 v224, 0, v224
	v_exp_f32_e32 v224, v224
	v_cmp_ge_i32_e32 vcc, 2, v179
	v_cndmask_b32_e64 v225, 0, v225, s[22:23]
	v_fma_f32 v227, v227, s41, -v212
	v_min_f32_e32 v227, 0, v227
	v_exp_f32_e32 v227, v227
	v_cmp_ge_i32_e64 s[22:23], 34, v179
	v_cndmask_b32_e32 v224, 0, v224, vcc
	v_fma_f32 v226, v226, s41, -v212
	v_min_f32_e32 v226, 0, v226
	v_exp_f32_e32 v226, v226
	v_cmp_ge_i32_e32 vcc, 3, v179
	v_cndmask_b32_e64 v227, 0, v227, s[22:23]
	v_fma_f32 v229, v229, s41, -v212
	v_min_f32_e32 v229, 0, v229
	v_exp_f32_e32 v229, v229
	v_cmp_ge_i32_e64 s[22:23], 35, v179
	v_cndmask_b32_e32 v226, 0, v226, vcc
	v_fma_f32 v228, v228, s41, -v212
	v_min_f32_e32 v228, 0, v228
	v_exp_f32_e32 v228, v228
	v_cmp_ge_i32_e32 vcc, 8, v179
	v_cndmask_b32_e64 v229, 0, v229, s[22:23]
	v_fma_f32 v231, v231, s41, -v212
	v_min_f32_e32 v231, 0, v231
	v_exp_f32_e32 v231, v231
	v_cmp_ge_i32_e64 s[22:23], 40, v179
	v_cndmask_b32_e32 v228, 0, v228, vcc
	v_fma_f32 v230, v230, s41, -v212
	v_min_f32_e32 v230, 0, v230
	v_exp_f32_e32 v230, v230
	v_cmp_ge_i32_e32 vcc, 9, v179
	v_cndmask_b32_e64 v231, 0, v231, s[22:23]
	v_fma_f32 v233, v233, s41, -v212
	v_min_f32_e32 v233, 0, v233
	v_exp_f32_e32 v233, v233
	v_cmp_ge_i32_e64 s[22:23], 41, v179
	v_cndmask_b32_e32 v230, 0, v230, vcc
	v_fma_f32 v232, v232, s41, -v212
	v_min_f32_e32 v232, 0, v232
	v_exp_f32_e32 v232, v232
	v_cmp_ge_i32_e32 vcc, 10, v179
	v_cndmask_b32_e64 v233, 0, v233, s[22:23]
	v_fma_f32 v235, v235, s41, -v212
	v_min_f32_e32 v235, 0, v235
	v_exp_f32_e32 v235, v235
	v_cmp_ge_i32_e64 s[22:23], 42, v179
	v_cndmask_b32_e32 v232, 0, v232, vcc
	v_fma_f32 v234, v234, s41, -v212
	v_min_f32_e32 v234, 0, v234
	v_exp_f32_e32 v234, v234
	v_cmp_ge_i32_e32 vcc, 11, v179
; __device__ __forceinline__ int crow(int r, int hi) { return (r & 3) + 8 * (r >> 2) + 4 * hi; }
; __device__ __forceinline__ void mlstm_item(const int tid0, const P& p, int item, char* lds) {
;     ...
;             for (int r = 0; r < 16; ++r) {
;                 const int s0 = 64 * kt + crow(r, hi), s1 = s0 + 32;
;                 const bool a0 = dir ? (s0 >= tl) : (s0 <= tl), a1 = dir ? (s1 >= tl) : (s1 <= tl);
;                 const float w0 = a0 ? __builtin_amdgcn_exp2f(fminf(su[s0] * 1.4426950408889634f - MtL, 0.f)) : 0.f;
;                 const float w1 = a1 ? __builtin_amdgcn_exp2f(fminf(su[s1] * 1.4426950408889634f - MtL, 0.f)) : 0.f;
;                 p0[r] *= w0; p1[r] *= w1; dsum += p0[r] + p1[r];
	v_cndmask_b32_e64 v235, 0, v235, s[22:23]
	v_fma_f32 v237, v237, s41, -v212
	v_min_f32_e32 v237, 0, v237
	v_exp_f32_e32 v237, v237
	v_cmp_ge_i32_e64 s[22:23], 43, v179
	v_cndmask_b32_e32 v234, 0, v234, vcc
	v_fma_f32 v236, v236, s41, -v212
	v_min_f32_e32 v236, 0, v236
	v_exp_f32_e32 v236, v236
	v_cmp_ge_i32_e32 vcc, 16, v179
	v_cndmask_b32_e64 v237, 0, v237, s[22:23]
	v_fma_f32 v239, v239, s41, -v212
	v_min_f32_e32 v239, 0, v239
	v_exp_f32_e32 v239, v239
	v_cmp_ge_i32_e64 s[22:23], 48, v179
	v_cndmask_b32_e32 v236, 0, v236, vcc
	v_fma_f32 v238, v238, s41, -v212
	v_min_f32_e32 v238, 0, v238
	v_exp_f32_e32 v238, v238
	v_cmp_ge_i32_e32 vcc, 17, v179
	v_cndmask_b32_e64 v239, 0, v239, s[22:23]
	v_fma_f32 v246, v246, s41, -v212
	v_min_f32_e32 v246, 0, v246
	v_exp_f32_e32 v246, v246
	v_cmp_ge_i32_e64 s[22:23], 49, v179
	v_cndmask_b32_e32 v238, 0, v238, vcc
	v_fma_f32 v245, v245, s41, -v212
	v_min_f32_e32 v245, 0, v245
	v_exp_f32_e32 v245, v245
	v_cmp_ge_i32_e32 vcc, 18, v179
	v_cndmask_b32_e64 v246, 0, v246, s[22:23]
	v_fma_f32 v248, v248, s41, -v212
	v_min_f32_e32 v248, 0, v248
	v_exp_f32_e32 v248, v248
	v_cmp_ge_i32_e64 s[22:23], 50, v179
	v_cndmask_b32_e32 v245, 0, v245, vcc
	v_fma_f32 v247, v247, s41, -v212
	v_min_f32_e32 v247, 0, v247
	v_exp_f32_e32 v247, v247
	v_cmp_ge_i32_e32 vcc, 19, v179
	v_cndmask_b32_e64 v248, 0, v248, s[22:23]
	v_fma_f32 v250, v250, s41, -v212
	v_min_f32_e32 v250, 0, v250
	v_exp_f32_e32 v250, v250
	v_cmp_ge_i32_e64 s[22:23], 51, v179
	v_cndmask_b32_e32 v247, 0, v247, vcc
	v_fma_f32 v249, v249, s41, -v212
	v_min_f32_e32 v249, 0, v249
	v_exp_f32_e32 v249, v249
	v_cmp_ge_i32_e32 vcc, 24, v179
	v_cndmask_b32_e64 v250, 0, v250, s[22:23]
	v_fma_f32 v252, v252, s41, -v212
	v_min_f32_e32 v252, 0, v252
	v_exp_f32_e32 v252, v252
	v_cmp_ge_i32_e64 s[22:23], 56, v179
	v_cndmask_b32_e32 v249, 0, v249, vcc
	v_fma_f32 v251, v251, s41, -v212
	v_min_f32_e32 v251, 0, v251
	v_exp_f32_e32 v251, v251
	v_cmp_ge_i32_e32 vcc, 25, v179
	v_cndmask_b32_e64 v252, 0, v252, s[22:23]
	v_fma_f32 v243, v243, s41, -v212
	v_min_f32_e32 v243, 0, v243
	v_exp_f32_e32 v243, v243
	v_cmp_ge_i32_e64 s[22:23], 57, v179
	v_cndmask_b32_e32 v251, 0, v251, vcc
	v_fma_f32 v253, v253, s41, -v212
	v_min_f32_e32 v253, 0, v253
	v_exp_f32_e32 v253, v253
	v_cmp_ge_i32_e32 vcc, 26, v179
	v_cndmask_b32_e64 v243, 0, v243, s[22:23]
	v_fma_f32 v240, v240, s41, -v212
	v_min_f32_e32 v240, 0, v240
	v_exp_f32_e32 v240, v240
	v_cmp_ge_i32_e64 s[22:23], 58, v179
	v_cndmask_b32_e32 v253, 0, v253, vcc
	v_fma_f32 v180, v180, s41, -v212
	v_min_f32_e32 v180, 0, v180
	v_exp_f32_e32 v180, v180
	v_cmp_ge_i32_e32 vcc, 27, v179
	v_cndmask_b32_e64 v240, 0, v240, s[22:23]
	v_fma_f32 v181, v181, s41, -v212
	v_min_f32_e32 v181, 0, v181
	v_exp_f32_e32 v181, v181
	v_cmp_ge_i32_e64 s[22:23], 59, v179
	v_cndmask_b32_e32 v180, 0, v180, vcc
	s_nop 1
	v_cndmask_b32_e64 v181, 0, v181, s[22:23]
; __device__ __forceinline__ void mlstm_item(const int tid0, const P& p, int item, char* lds) {
;     ...
;                 p0[r] *= w0; p1[r] *= w1; dsum += p0[r] + p1[r];
;             }
;             bf16x8 pa0, pa1, pa2, pa3;
;             PK4(p0, 0, pa0); PK4(p0, 8, pa1); PK4(p1, 0, pa2); PK4(p1, 8, pa3);
;             if (kt == 0) { pv_one<0, 0>(o0, vbV, pa0, pa1, pa2, pa3); pv_one<1, 0>(o1, vbV, pa0, pa1, pa2, pa3); }
;             else         { pv_one<0, 16384>(o0, vbV, pa0, pa1, pa2, pa3); pv_one<1, 16384>(o1, vbV, pa0, pa1, pa2, pa3); }
.Lmlw_done_k0:
.LBB0_234:
	v_mul_f32_e32 v223, v82, v223
	v_fma_f32 v82, v98, v222, v223
	v_mul_f32_e32 v225, v83, v225
	v_mul_f32_e32 v241, v98, v222
	v_add_f32_e32 v82, 0, v82
	v_mul_f32_e32 v222, v99, v221
	v_fma_f32 v83, v99, v221, v225
	v_mul_f32_e32 v221, v84, v227
	v_add_f32_e32 v82, v82, v83
	v_mul_f32_e32 v83, v100, v224
	v_fma_f32 v84, v100, v224, v221
	v_mul_f32_e32 v100, v85, v229
	v_add_f32_e32 v82, v82, v84
	v_mul_f32_e32 v84, v101, v226
	v_fma_f32 v85, v101, v226, v100
	v_mul_f32_e32 v101, v86, v231
	v_add_f32_e32 v82, v82, v85
	v_mul_f32_e32 v85, v102, v228
	v_fma_f32 v86, v102, v228, v101
	v_mul_f32_e32 v102, v87, v233
	v_add_f32_e32 v82, v82, v86
	v_mul_f32_e32 v86, v103, v230
	v_fma_f32 v87, v103, v230, v102
	v_mul_f32_e32 v103, v88, v235
	v_add_f32_e32 v82, v82, v87
	v_mul_f32_e32 v87, v104, v232
	v_fma_f32 v88, v104, v232, v103
	v_mul_f32_e32 v104, v89, v237
	v_add_f32_e32 v82, v82, v88
	v_mul_f32_e32 v88, v105, v234
	v_fma_f32 v89, v105, v234, v104
	v_mul_f32_e32 v105, v90, v239
	v_add_f32_e32 v82, v82, v89
	v_mul_f32_e32 v89, v106, v236
	v_fma_f32 v90, v106, v236, v105
	v_mul_f32_e32 v106, v91, v246
	v_add_f32_e32 v82, v82, v90
	v_mul_f32_e32 v90, v107, v238
	v_fma_f32 v91, v107, v238, v106
	v_mul_f32_e32 v107, v92, v248
	v_add_f32_e32 v82, v82, v91
	v_mul_f32_e32 v91, v108, v245
	v_fma_f32 v92, v108, v245, v107
	v_mul_f32_e32 v108, v93, v250
	v_add_f32_e32 v82, v82, v92
	v_mul_f32_e32 v92, v109, v247
	v_fma_f32 v93, v109, v247, v108
	v_mul_f32_e32 v109, v94, v252
	v_add_f32_e32 v82, v82, v93
	v_mul_f32_e32 v93, v110, v249
	v_fma_f32 v94, v110, v249, v109
	v_mul_f32_e32 v110, v95, v243
	v_add_f32_e32 v82, v82, v94
	v_mul_f32_e32 v94, v111, v251
	v_fma_f32 v95, v111, v251, v110
	v_mul_f32_e32 v111, v96, v240
	v_add_f32_e32 v82, v82, v95
	v_fma_f32 v96, v112, v253, v111
	v_mul_f32_e32 v95, v112, v253
	v_add_f32_e32 v112, v82, v96
	v_mov_b32_e32 v96, v113
	v_pk_mul_f32 v[98:99], v[96:97], v[180:181]
	v_cvt_pk_bf16_f32 v82, v241, v222
	v_cvt_pk_bf16_f32 v83, v83, v84
	v_cvt_pk_bf16_f32 v84, v85, v86
	v_cvt_pk_bf16_f32 v85, v87, v88
	v_cvt_pk_bf16_f32 v86, v89, v90
	v_cvt_pk_bf16_f32 v87, v91, v92
	v_cvt_pk_bf16_f32 v88, v93, v94
	s_nop 0
	v_cvt_pk_bf16_f32 v89, v95, v98
	v_add_f32_e32 v98, v98, v99
	v_cvt_pk_bf16_f32 v90, v223, v225
	v_cvt_pk_bf16_f32 v91, v221, v100
	v_cvt_pk_bf16_f32 v92, v101, v102
	v_cvt_pk_bf16_f32 v93, v103, v104
	v_cvt_pk_bf16_f32 v94, v105, v106
	v_cvt_pk_bf16_f32 v95, v107, v108
	v_cvt_pk_bf16_f32 v96, v109, v110
	v_cvt_pk_bf16_f32 v97, v111, v99
	v_add_f32_e32 v180, v112, v98
	ds_read_b64_tr_b16 v[98:99], v203 offset:0
	ds_read_b64_tr_b16 v[100:101], v203 offset:0x800
	ds_read_b64_tr_b16 v[102:103], v203 offset:0x1000
	ds_read_b64_tr_b16 v[104:105], v203 offset:0x1800
	ds_read_b64_tr_b16 v[106:107], v203 offset:0x2000
	ds_read_b64_tr_b16 v[108:109], v203 offset:0x2800
	ds_read_b64_tr_b16 v[110:111], v203 offset:0x3000
	ds_read_b64_tr_b16 v[112:113], v203 offset:0x3800
	s_waitcnt lgkmcnt(0)
	v_permlane32_swap_b32_e32 v82, v84
	v_permlane32_swap_b32_e32 v83, v85
	v_permlane32_swap_b32_e32 v86, v88
	v_permlane32_swap_b32_e32 v87, v89
	v_permlane32_swap_b32_e32 v90, v92
	v_permlane32_swap_b32_e32 v91, v93
	v_permlane32_swap_b32_e32 v94, v96
	v_permlane32_swap_b32_e32 v95, v97
	v_mfma_f32_32x32x16_bf16 v[50:65], v[82:85], v[98:101], v[50:65]
	ds_read_b64_tr_b16 v[98:99], v203 offset:0x200
	ds_read_b64_tr_b16 v[100:101], v203 offset:0xa00
	v_mfma_f32_32x32x16_bf16 v[50:65], v[86:89], v[102:105], v[50:65]
	ds_read_b64_tr_b16 v[102:103], v203 offset:0x1200
	ds_read_b64_tr_b16 v[104:105], v203 offset:0x1a00
	v_mfma_f32_32x32x16_bf16 v[50:65], v[90:93], v[106:109], v[50:65]
	ds_read_b64_tr_b16 v[106:107], v203 offset:0x2200
	ds_read_b64_tr_b16 v[108:109], v203 offset:0x2a00
	v_mfma_f32_32x32x16_bf16 v[50:65], v[94:97], v[110:113], v[50:65]
	ds_read_b64_tr_b16 v[110:111], v203 offset:0x3200
	ds_read_b64_tr_b16 v[112:113], v203 offset:0x3a00
	s_waitcnt lgkmcnt(0)
	v_mfma_f32_32x32x16_bf16 v[66:81], v[82:85], v[98:101], v[66:81]
	v_mfma_f32_32x32x16_bf16 v[66:81], v[86:89], v[102:105], v[66:81]
	v_mfma_f32_32x32x16_bf16 v[66:81], v[90:93], v[106:109], v[66:81]
	v_mfma_f32_32x32x16_bf16 v[66:81], v[94:97], v[110:113], v[66:81]
	s_andn2_b64 vcc, exec, s[36:37]
	s_cbranch_vccz .LBB0_236
	s_branch .LBB0_301

; __device__ __forceinline__ int crow(int r, int hi) { return (r & 3) + 8 * (r >> 2) + 4 * hi; }
; __device__ __forceinline__ void mlstm_item(const int tid0, const P& p, int item, char* lds) {
;     ...
;             qkt(p0, p1, Ks + kt * 16384, qr, r32, hi);
; #pragma unroll
;             for (int r = 0; r < 16; ++r) {
;                 const int s0 = 64 * kt + crow(r, hi), s1 = s0 + 32;
;                 const bool a0 = dir ? (s0 >= tl) : (s0 <= tl), a1 = dir ? (s1 >= tl) : (s1 <= tl);
;                 const float w0 = a0 ? __builtin_amdgcn_exp2f(fminf(su[s0] * 1.4426950408889634f - MtL, 0.f)) : 0.f;
;                 const float w1 = a1 ? __builtin_amdgcn_exp2f(fminf(su[s1] * 1.4426950408889634f - MtL, 0.f)) : 0.f;
.LBB0_236:
	ds_read_b128 v[82:85], v220 offset:16384
	ds_read_b128 v[86:89], v220 offset:24576
	s_waitcnt lgkmcnt(1)
	v_mfma_f32_32x32x16_bf16 v[98:113], v[82:85], v[174:177], 0
	s_waitcnt lgkmcnt(0)
	v_mfma_f32_32x32x16_bf16 v[82:97], v[86:89], v[174:177], 0
	ds_read_b128 v[174:177], v219 offset:16384
	ds_read_b128 v[220:223], v219 offset:24576
	s_waitcnt lgkmcnt(1)
	v_mfma_f32_32x32x16_bf16 v[98:113], v[174:177], v[170:173], v[98:113]
	s_waitcnt lgkmcnt(0)
	v_mfma_f32_32x32x16_bf16 v[82:97], v[220:223], v[170:173], v[82:97]
	ds_read_b128 v[170:173], v218 offset:16384
	ds_read_b128 v[174:177], v218 offset:24576
	s_waitcnt lgkmcnt(1)
	v_mfma_f32_32x32x16_bf16 v[98:113], v[170:173], v[166:169], v[98:113]
	s_waitcnt lgkmcnt(0)
	v_mfma_f32_32x32x16_bf16 v[82:97], v[174:177], v[166:169], v[82:97]
	ds_read_b128 v[166:169], v217 offset:16384
	ds_read_b128 v[170:173], v217 offset:24576
	s_waitcnt lgkmcnt(1)
	v_mfma_f32_32x32x16_bf16 v[98:113], v[166:169], v[162:165], v[98:113]
	s_waitcnt lgkmcnt(0)
	v_mfma_f32_32x32x16_bf16 v[82:97], v[170:173], v[162:165], v[82:97]
	ds_read_b128 v[162:165], v216 offset:16384
	ds_read_b128 v[166:169], v216 offset:24576
	s_waitcnt lgkmcnt(1)
	v_mfma_f32_32x32x16_bf16 v[98:113], v[162:165], v[158:161], v[98:113]
	s_waitcnt lgkmcnt(0)
	v_mfma_f32_32x32x16_bf16 v[82:97], v[166:169], v[158:161], v[82:97]
	ds_read_b128 v[158:161], v215 offset:16384
	ds_read_b128 v[162:165], v215 offset:24576
	s_waitcnt lgkmcnt(1)
	v_mfma_f32_32x32x16_bf16 v[98:113], v[158:161], v[154:157], v[98:113]
	s_waitcnt lgkmcnt(0)
	v_mfma_f32_32x32x16_bf16 v[82:97], v[162:165], v[154:157], v[82:97]
	ds_read_b128 v[154:157], v214 offset:16384
	ds_read_b128 v[158:161], v214 offset:24576
	s_waitcnt lgkmcnt(1)
	v_mfma_f32_32x32x16_bf16 v[98:113], v[154:157], v[150:153], v[98:113]
	s_waitcnt lgkmcnt(0)
	v_mfma_f32_32x32x16_bf16 v[82:97], v[158:161], v[150:153], v[82:97]
	ds_read_b128 v[154:157], v213 offset:16384
	ds_read_b128 v[158:161], v213 offset:24576
	v_or_b32_e32 v152, 64, v211
	v_cmp_le_u32_e32 vcc, v152, v201
	s_nop 1
	v_cndmask_b32_e64 v150, 0, 1, vcc
	v_cmp_ge_u32_e32 vcc, v152, v201
	s_waitcnt lgkmcnt(1)
	v_mfma_f32_32x32x16_bf16 v[98:113], v[154:157], v[146:149], v[98:113]
	v_cndmask_b32_e64 v151, 0, 1, vcc
	v_cndmask_b32_e64 v150, v151, v150, s[4:5]
	v_and_b32_e32 v150, 1, v150
	v_cmp_eq_u32_e32 vcc, 1, v150
	v_mov_b32_e32 v150, 0
	v_mov_b32_e32 v151, 0
	s_waitcnt lgkmcnt(0)
	v_mfma_f32_32x32x16_bf16 v[82:97], v[158:161], v[146:149], v[82:97]
	v_lshl_add_u32 v181, v211, 2, 0
	v_add_u32_e32 v181, 0x20200, v181
	ds_read_b32 v151, v181 offset:256
	ds_read_b32 v148, v181 offset:384
	ds_read_b32 v150, v181 offset:260
	ds_read_b32 v152, v181 offset:388
	ds_read_b32 v149, v181 offset:264
	ds_read_b32 v154, v181 offset:392
	ds_read_b32 v153, v181 offset:268
	ds_read_b32 v156, v181 offset:396
	ds_read_b32 v155, v181 offset:288
	ds_read_b32 v158, v181 offset:416
	ds_read_b32 v157, v181 offset:292
	ds_read_b32 v160, v181 offset:420
	ds_read_b32 v159, v181 offset:296
	ds_read_b32 v162, v181 offset:424
	ds_read_b32 v161, v181 offset:300
	ds_read_b32 v164, v181 offset:428
	ds_read_b32 v163, v181 offset:320
	ds_read_b32 v166, v181 offset:448
	ds_read_b32 v165, v181 offset:324
	ds_read_b32 v168, v181 offset:452
	ds_read_b32 v167, v181 offset:328
	ds_read_b32 v170, v181 offset:456
	ds_read_b32 v169, v181 offset:332
	ds_read_b32 v172, v181 offset:460
	ds_read_b32 v171, v181 offset:352
	ds_read_b32 v174, v181 offset:480
	ds_read_b32 v173, v181 offset:356
	ds_read_b32 v176, v181 offset:484
	ds_read_b32 v175, v181 offset:360
	ds_read_b32 v177, v181 offset:488
	ds_read_b32 v146, v181 offset:364
	ds_read_b32 v147, v181 offset:492
	v_sub_u32_e32 v179, v201, v211
	v_subrev_u32_e32 v179, 64, v179
	s_waitcnt lgkmcnt(0)
	s_cmp_lg_u64 s[4:5], 0
	s_cbranch_scc0 .Lmlw_d1_k1
	v_fma_f32 v151, v151, s41, -v212
	v_min_f32_e32 v151, 0, v151
	v_exp_f32_e32 v151, v151
	v_cmp_le_i32_e32 vcc, 0, v179
	v_fma_f32 v148, v148, s41, -v212
	v_min_f32_e32 v148, 0, v148
	v_exp_f32_e32 v148, v148
	v_cmp_le_i32_e64 s[22:23], 32, v179
	v_cndmask_b32_e32 v151, 0, v151, vcc
	v_fma_f32 v150, v150, s41, -v212
	v_min_f32_e32 v150, 0, v150
	v_exp_f32_e32 v150, v150
	v_cmp_le_i32_e32 vcc, 1, v179
	v_cndmask_b32_e64 v148, 0, v148, s[22:23]
	v_fma_f32 v152, v152, s41, -v212
	v_min_f32_e32 v152, 0, v152
	v_exp_f32_e32 v152, v152
	v_cmp_le_i32_e64 s[22:23], 33, v179
	v_cndmask_b32_e32 v150, 0, v150, vcc
	v_fma_f32 v149, v149, s41, -v212
	v_min_f32_e32 v149, 0, v149
	v_exp_f32_e32 v149, v149
	v_cmp_le_i32_e32 vcc, 2, v179
	v_cndmask_b32_e64 v152, 0, v152, s[22:23]
	v_fma_f32 v154, v154, s41, -v212
	v_min_f32_e32 v154, 0, v154
	v_exp_f32_e32 v154, v154
	v_cmp_le_i32_e64 s[22:23], 34, v179
	v_cndmask_b32_e32 v149, 0, v149, vcc
	v_fma_f32 v153, v153, s41, -v212
	v_min_f32_e32 v153, 0, v153
	v_exp_f32_e32 v153, v153
	v_cmp_le_i32_e32 vcc, 3, v179
	v_cndmask_b32_e64 v154, 0, v154, s[22:23]
	v_fma_f32 v156, v156, s41, -v212
	v_min_f32_e32 v156, 0, v156
	v_exp_f32_e32 v156, v156
	v_cmp_le_i32_e64 s[22:23], 35, v179
	v_cndmask_b32_e32 v153, 0, v153, vcc
	v_fma_f32 v155, v155, s41, -v212
	v_min_f32_e32 v155, 0, v155
	v_exp_f32_e32 v155, v155
	v_cmp_le_i32_e32 vcc, 8, v179
	v_cndmask_b32_e64 v156, 0, v156, s[22:23]
	v_fma_f32 v158, v158, s41, -v212
	v_min_f32_e32 v158, 0, v158
	v_exp_f32_e32 v158, v158
	v_cmp_le_i32_e64 s[22:23], 40, v179
	v_cndmask_b32_e32 v155, 0, v155, vcc
	v_fma_f32 v157, v157, s41, -v212
	v_min_f32_e32 v157, 0, v157
	v_exp_f32_e32 v157, v157
	v_cmp_le_i32_e32 vcc, 9, v179
	v_cndmask_b32_e64 v158, 0, v158, s[22:23]
	v_fma_f32 v160, v160, s41, -v212
	v_min_f32_e32 v160, 0, v160
; __device__ __forceinline__ int crow(int r, int hi) { return (r & 3) + 8 * (r >> 2) + 4 * hi; }
; __device__ __forceinline__ void mlstm_item(const int tid0, const P& p, int item, char* lds) {
;     ...
;             for (int r = 0; r < 16; ++r) {
;                 const int s0 = 64 * kt + crow(r, hi), s1 = s0 + 32;
;                 const bool a0 = dir ? (s0 >= tl) : (s0 <= tl), a1 = dir ? (s1 >= tl) : (s1 <= tl);
;                 const float w0 = a0 ? __builtin_amdgcn_exp2f(fminf(su[s0] * 1.4426950408889634f - MtL, 0.f)) : 0.f;
;                 const float w1 = a1 ? __builtin_amdgcn_exp2f(fminf(su[s1] * 1.4426950408889634f - MtL, 0.f)) : 0.f;
;                 p0[r] *= w0; p1[r] *= w1; dsum += p0[r] + p1[r];
	v_exp_f32_e32 v160, v160
	v_cmp_le_i32_e64 s[22:23], 41, v179
	v_cndmask_b32_e32 v157, 0, v157, vcc
	v_fma_f32 v159, v159, s41, -v212
	v_min_f32_e32 v159, 0, v159
	v_exp_f32_e32 v159, v159
	v_cmp_le_i32_e32 vcc, 10, v179
	v_cndmask_b32_e64 v160, 0, v160, s[22:23]
	v_fma_f32 v162, v162, s41, -v212
	v_min_f32_e32 v162, 0, v162
	v_exp_f32_e32 v162, v162
	v_cmp_le_i32_e64 s[22:23], 42, v179
	v_cndmask_b32_e32 v159, 0, v159, vcc
	v_fma_f32 v161, v161, s41, -v212
	v_min_f32_e32 v161, 0, v161
	v_exp_f32_e32 v161, v161
	v_cmp_le_i32_e32 vcc, 11, v179
	v_cndmask_b32_e64 v162, 0, v162, s[22:23]
	v_fma_f32 v164, v164, s41, -v212
	v_min_f32_e32 v164, 0, v164
	v_exp_f32_e32 v164, v164
	v_cmp_le_i32_e64 s[22:23], 43, v179
	v_cndmask_b32_e32 v161, 0, v161, vcc
	v_fma_f32 v163, v163, s41, -v212
	v_min_f32_e32 v163, 0, v163
	v_exp_f32_e32 v163, v163
	v_cmp_le_i32_e32 vcc, 16, v179
	v_cndmask_b32_e64 v164, 0, v164, s[22:23]
	v_fma_f32 v166, v166, s41, -v212
	v_min_f32_e32 v166, 0, v166
	v_exp_f32_e32 v166, v166
	v_cmp_le_i32_e64 s[22:23], 48, v179
	v_cndmask_b32_e32 v163, 0, v163, vcc
	v_fma_f32 v165, v165, s41, -v212
	v_min_f32_e32 v165, 0, v165
	v_exp_f32_e32 v165, v165
	v_cmp_le_i32_e32 vcc, 17, v179
	v_cndmask_b32_e64 v166, 0, v166, s[22:23]
	v_fma_f32 v168, v168, s41, -v212
	v_min_f32_e32 v168, 0, v168
	v_exp_f32_e32 v168, v168
	v_cmp_le_i32_e64 s[22:23], 49, v179
	v_cndmask_b32_e32 v165, 0, v165, vcc
	v_fma_f32 v167, v167, s41, -v212
	v_min_f32_e32 v167, 0, v167
	v_exp_f32_e32 v167, v167
	v_cmp_le_i32_e32 vcc, 18, v179
	v_cndmask_b32_e64 v168, 0, v168, s[22:23]
	v_fma_f32 v170, v170, s41, -v212
	v_min_f32_e32 v170, 0, v170
	v_exp_f32_e32 v170, v170
	v_cmp_le_i32_e64 s[22:23], 50, v179
	v_cndmask_b32_e32 v167, 0, v167, vcc
	v_fma_f32 v169, v169, s41, -v212
	v_min_f32_e32 v169, 0, v169
	v_exp_f32_e32 v169, v169
	v_cmp_le_i32_e32 vcc, 19, v179
	v_cndmask_b32_e64 v170, 0, v170, s[22:23]
	v_fma_f32 v172, v172, s41, -v212
	v_min_f32_e32 v172, 0, v172
	v_exp_f32_e32 v172, v172
	v_cmp_le_i32_e64 s[22:23], 51, v179
	v_cndmask_b32_e32 v169, 0, v169, vcc
	v_fma_f32 v171, v171, s41, -v212
	v_min_f32_e32 v171, 0, v171
	v_exp_f32_e32 v171, v171
	v_cmp_le_i32_e32 vcc, 24, v179
	v_cndmask_b32_e64 v172, 0, v172, s[22:23]
	v_fma_f32 v174, v174, s41, -v212
	v_min_f32_e32 v174, 0, v174
	v_exp_f32_e32 v174, v174
	v_cmp_le_i32_e64 s[22:23], 56, v179
	v_cndmask_b32_e32 v171, 0, v171, vcc
	v_fma_f32 v173, v173, s41, -v212
	v_min_f32_e32 v173, 0, v173
	v_exp_f32_e32 v173, v173
	v_cmp_le_i32_e32 vcc, 25, v179
	v_cndmask_b32_e64 v174, 0, v174, s[22:23]
	v_fma_f32 v176, v176, s41, -v212
	v_min_f32_e32 v176, 0, v176
	v_exp_f32_e32 v176, v176
	v_cmp_le_i32_e64 s[22:23], 57, v179
	v_cndmask_b32_e32 v173, 0, v173, vcc
	v_fma_f32 v175, v175, s41, -v212
	v_min_f32_e32 v175, 0, v175
	v_exp_f32_e32 v175, v175
	v_cmp_le_i32_e32 vcc, 26, v179
	v_cndmask_b32_e64 v176, 0, v176, s[22:23]
	v_fma_f32 v177, v177, s41, -v212
	v_min_f32_e32 v177, 0, v177
	v_exp_f32_e32 v177, v177
	v_cmp_le_i32_e64 s[22:23], 58, v179
	v_cndmask_b32_e32 v175, 0, v175, vcc
	v_fma_f32 v146, v146, s41, -v212
	v_min_f32_e32 v146, 0, v146
	v_exp_f32_e32 v146, v146
	v_cmp_le_i32_e32 vcc, 27, v179
	v_cndmask_b32_e64 v177, 0, v177, s[22:23]
	v_fma_f32 v147, v147, s41, -v212
	v_min_f32_e32 v147, 0, v147
	v_exp_f32_e32 v147, v147
	v_cmp_le_i32_e64 s[22:23], 59, v179
	v_cndmask_b32_e32 v146, 0, v146, vcc
	s_nop 1
	v_cndmask_b32_e64 v147, 0, v147, s[22:23]
	s_branch .Lmlw_done_k1
.Lmlw_d1_k1:
	v_fma_f32 v151, v151, s41, -v212
	v_min_f32_e32 v151, 0, v151
	v_exp_f32_e32 v151, v151
	v_cmp_ge_i32_e32 vcc, 0, v179
	v_fma_f32 v148, v148, s41, -v212
	v_min_f32_e32 v148, 0, v148
	v_exp_f32_e32 v148, v148
	v_cmp_ge_i32_e64 s[22:23], 32, v179
	v_cndmask_b32_e32 v151, 0, v151, vcc
	v_fma_f32 v150, v150, s41, -v212
	v_min_f32_e32 v150, 0, v150
	v_exp_f32_e32 v150, v150
	v_cmp_ge_i32_e32 vcc, 1, v179
	v_cndmask_b32_e64 v148, 0, v148, s[22:23]
	v_fma_f32 v152, v152, s41, -v212
	v_min_f32_e32 v152, 0, v152
	v_exp_f32_e32 v152, v152
	v_cmp_ge_i32_e64 s[22:23], 33, v179
	v_cndmask_b32_e32 v150, 0, v150, vcc
	v_fma_f32 v149, v149, s41, -v212
	v_min_f32_e32 v149, 0, v149
	v_exp_f32_e32 v149, v149
	v_cmp_ge_i32_e32 vcc, 2, v179
	v_cndmask_b32_e64 v152, 0, v152, s[22:23]
	v_fma_f32 v154, v154, s41, -v212
	v_min_f32_e32 v154, 0, v154
	v_exp_f32_e32 v154, v154
	v_cmp_ge_i32_e64 s[22:23], 34, v179
	v_cndmask_b32_e32 v149, 0, v149, vcc
	v_fma_f32 v153, v153, s41, -v212
	v_min_f32_e32 v153, 0, v153
	v_exp_f32_e32 v153, v153
	v_cmp_ge_i32_e32 vcc, 3, v179
	v_cndmask_b32_e64 v154, 0, v154, s[22:23]
	v_fma_f32 v156, v156, s41, -v212
	v_min_f32_e32 v156, 0, v156
	v_exp_f32_e32 v156, v156
	v_cmp_ge_i32_e64 s[22:23], 35, v179
	v_cndmask_b32_e32 v153, 0, v153, vcc
	v_fma_f32 v155, v155, s41, -v212
	v_min_f32_e32 v155, 0, v155
	v_exp_f32_e32 v155, v155
	v_cmp_ge_i32_e32 vcc, 8, v179
	v_cndmask_b32_e64 v156, 0, v156, s[22:23]
	v_fma_f32 v158, v158, s41, -v212
	v_min_f32_e32 v158, 0, v158
	v_exp_f32_e32 v158, v158
	v_cmp_ge_i32_e64 s[22:23], 40, v179
	v_cndmask_b32_e32 v155, 0, v155, vcc
	v_fma_f32 v157, v157, s41, -v212
	v_min_f32_e32 v157, 0, v157
	v_exp_f32_e32 v157, v157
	v_cmp_ge_i32_e32 vcc, 9, v179
	v_cndmask_b32_e64 v158, 0, v158, s[22:23]
	v_fma_f32 v160, v160, s41, -v212
	v_min_f32_e32 v160, 0, v160
	v_exp_f32_e32 v160, v160
	v_cmp_ge_i32_e64 s[22:23], 41, v179
	v_cndmask_b32_e32 v157, 0, v157, vcc
	v_fma_f32 v159, v159, s41, -v212
	v_min_f32_e32 v159, 0, v159
	v_exp_f32_e32 v159, v159
	v_cmp_ge_i32_e32 vcc, 10, v179
	v_cndmask_b32_e64 v160, 0, v160, s[22:23]
	v_fma_f32 v162, v162, s41, -v212
	v_min_f32_e32 v162, 0, v162
	v_exp_f32_e32 v162, v162
; __device__ __forceinline__ int crow(int r, int hi) { return (r & 3) + 8 * (r >> 2) + 4 * hi; }
; __device__ __forceinline__ void mlstm_item(const int tid0, const P& p, int item, char* lds) {
;     ...
;             for (int r = 0; r < 16; ++r) {
;                 const int s0 = 64 * kt + crow(r, hi), s1 = s0 + 32;
;                 const bool a0 = dir ? (s0 >= tl) : (s0 <= tl), a1 = dir ? (s1 >= tl) : (s1 <= tl);
;                 const float w0 = a0 ? __builtin_amdgcn_exp2f(fminf(su[s0] * 1.4426950408889634f - MtL, 0.f)) : 0.f;
;                 const float w1 = a1 ? __builtin_amdgcn_exp2f(fminf(su[s1] * 1.4426950408889634f - MtL, 0.f)) : 0.f;
;                 p0[r] *= w0; p1[r] *= w1; dsum += p0[r] + p1[r];
	v_cmp_ge_i32_e64 s[22:23], 42, v179
	v_cndmask_b32_e32 v159, 0, v159, vcc
	v_fma_f32 v161, v161, s41, -v212
	v_min_f32_e32 v161, 0, v161
	v_exp_f32_e32 v161, v161
	v_cmp_ge_i32_e32 vcc, 11, v179
	v_cndmask_b32_e64 v162, 0, v162, s[22:23]
	v_fma_f32 v164, v164, s41, -v212
	v_min_f32_e32 v164, 0, v164
	v_exp_f32_e32 v164, v164
	v_cmp_ge_i32_e64 s[22:23], 43, v179
	v_cndmask_b32_e32 v161, 0, v161, vcc
	v_fma_f32 v163, v163, s41, -v212
	v_min_f32_e32 v163, 0, v163
	v_exp_f32_e32 v163, v163
	v_cmp_ge_i32_e32 vcc, 16, v179
	v_cndmask_b32_e64 v164, 0, v164, s[22:23]
	v_fma_f32 v166, v166, s41, -v212
	v_min_f32_e32 v166, 0, v166
	v_exp_f32_e32 v166, v166
	v_cmp_ge_i32_e64 s[22:23], 48, v179
	v_cndmask_b32_e32 v163, 0, v163, vcc
	v_fma_f32 v165, v165, s41, -v212
	v_min_f32_e32 v165, 0, v165
	v_exp_f32_e32 v165, v165
	v_cmp_ge_i32_e32 vcc, 17, v179
	v_cndmask_b32_e64 v166, 0, v166, s[22:23]
	v_fma_f32 v168, v168, s41, -v212
	v_min_f32_e32 v168, 0, v168
	v_exp_f32_e32 v168, v168
	v_cmp_ge_i32_e64 s[22:23], 49, v179
	v_cndmask_b32_e32 v165, 0, v165, vcc
	v_fma_f32 v167, v167, s41, -v212
	v_min_f32_e32 v167, 0, v167
	v_exp_f32_e32 v167, v167
	v_cmp_ge_i32_e32 vcc, 18, v179
	v_cndmask_b32_e64 v168, 0, v168, s[22:23]
	v_fma_f32 v170, v170, s41, -v212
	v_min_f32_e32 v170, 0, v170
	v_exp_f32_e32 v170, v170
	v_cmp_ge_i32_e64 s[22:23], 50, v179
	v_cndmask_b32_e32 v167, 0, v167, vcc
	v_fma_f32 v169, v169, s41, -v212
	v_min_f32_e32 v169, 0, v169
	v_exp_f32_e32 v169, v169
	v_cmp_ge_i32_e32 vcc, 19, v179
	v_cndmask_b32_e64 v170, 0, v170, s[22:23]
	v_fma_f32 v172, v172, s41, -v212
	v_min_f32_e32 v172, 0, v172
	v_exp_f32_e32 v172, v172
	v_cmp_ge_i32_e64 s[22:23], 51, v179
	v_cndmask_b32_e32 v169, 0, v169, vcc
	v_fma_f32 v171, v171, s41, -v212
	v_min_f32_e32 v171, 0, v171
	v_exp_f32_e32 v171, v171
	v_cmp_ge_i32_e32 vcc, 24, v179
	v_cndmask_b32_e64 v172, 0, v172, s[22:23]
	v_fma_f32 v174, v174, s41, -v212
	v_min_f32_e32 v174, 0, v174
	v_exp_f32_e32 v174, v174
	v_cmp_ge_i32_e64 s[22:23], 56, v179
	v_cndmask_b32_e32 v171, 0, v171, vcc
	v_fma_f32 v173, v173, s41, -v212
	v_min_f32_e32 v173, 0, v173
	v_exp_f32_e32 v173, v173
	v_cmp_ge_i32_e32 vcc, 25, v179
	v_cndmask_b32_e64 v174, 0, v174, s[22:23]
	v_fma_f32 v176, v176, s41, -v212
	v_min_f32_e32 v176, 0, v176
	v_exp_f32_e32 v176, v176
	v_cmp_ge_i32_e64 s[22:23], 57, v179
	v_cndmask_b32_e32 v173, 0, v173, vcc
	v_fma_f32 v175, v175, s41, -v212
	v_min_f32_e32 v175, 0, v175
	v_exp_f32_e32 v175, v175
	v_cmp_ge_i32_e32 vcc, 26, v179
	v_cndmask_b32_e64 v176, 0, v176, s[22:23]
	v_fma_f32 v177, v177, s41, -v212
	v_min_f32_e32 v177, 0, v177
	v_exp_f32_e32 v177, v177
	v_cmp_ge_i32_e64 s[22:23], 58, v179
	v_cndmask_b32_e32 v175, 0, v175, vcc
	v_fma_f32 v146, v146, s41, -v212
	v_min_f32_e32 v146, 0, v146
	v_exp_f32_e32 v146, v146
	v_cmp_ge_i32_e32 vcc, 27, v179
	v_cndmask_b32_e64 v177, 0, v177, s[22:23]
	v_fma_f32 v147, v147, s41, -v212
	v_min_f32_e32 v147, 0, v147
	v_exp_f32_e32 v147, v147
	v_cmp_ge_i32_e64 s[22:23], 59, v179
	v_cndmask_b32_e32 v146, 0, v146, vcc
	s_nop 1
	v_cndmask_b32_e64 v147, 0, v147, s[22:23]
; __device__ __forceinline__ void mlstm_item(const int tid0, const P& p, int item, char* lds) {
;     ...
;                 p0[r] *= w0; p1[r] *= w1; dsum += p0[r] + p1[r];
;             }
;             bf16x8 pa0, pa1, pa2, pa3;
;             PK4(p0, 0, pa0); PK4(p0, 8, pa1); PK4(p1, 0, pa2); PK4(p1, 8, pa3);
;             if (kt == 0) { pv_one<0, 0>(o0, vbV, pa0, pa1, pa2, pa3); pv_one<1, 0>(o1, vbV, pa0, pa1, pa2, pa3); }
;             else         { pv_one<0, 16384>(o0, vbV, pa0, pa1, pa2, pa3); pv_one<1, 16384>(o1, vbV, pa0, pa1, pa2, pa3); }
;         }
;         dsum = xadd<32>(dsum);
.Lmlw_done_k1:
.LBB0_300:
	v_mul_f32_e32 v148, v82, v148
	v_fma_f32 v82, v98, v151, v148
	v_mul_f32_e32 v152, v83, v152
	v_mul_f32_e32 v181, v98, v151
	v_add_f32_e32 v82, v180, v82
	v_mul_f32_e32 v151, v99, v150
	v_fma_f32 v83, v99, v150, v152
	v_mul_f32_e32 v150, v84, v154
	v_add_f32_e32 v82, v82, v83
	v_mul_f32_e32 v83, v100, v149
	v_fma_f32 v84, v100, v149, v150
	v_mul_f32_e32 v100, v85, v156
	v_add_f32_e32 v82, v82, v84
	v_mul_f32_e32 v84, v101, v153
	v_fma_f32 v85, v101, v153, v100
	v_mul_f32_e32 v101, v86, v158
	v_add_f32_e32 v82, v82, v85
	v_mul_f32_e32 v85, v102, v155
	v_fma_f32 v86, v102, v155, v101
	v_mul_f32_e32 v102, v87, v160
	v_add_f32_e32 v82, v82, v86
	v_mul_f32_e32 v86, v103, v157
	v_fma_f32 v87, v103, v157, v102
	v_mul_f32_e32 v103, v88, v162
	v_add_f32_e32 v82, v82, v87
	v_mul_f32_e32 v87, v104, v159
	v_fma_f32 v88, v104, v159, v103
	v_mul_f32_e32 v104, v89, v164
	v_add_f32_e32 v82, v82, v88
	v_mul_f32_e32 v88, v105, v161
	v_fma_f32 v89, v105, v161, v104
	v_mul_f32_e32 v105, v90, v166
	v_add_f32_e32 v82, v82, v89
	v_mul_f32_e32 v89, v106, v163
	v_fma_f32 v90, v106, v163, v105
	v_mul_f32_e32 v106, v91, v168
	v_add_f32_e32 v82, v82, v90
	v_mul_f32_e32 v90, v107, v165
	v_fma_f32 v91, v107, v165, v106
	v_mul_f32_e32 v107, v92, v170
	v_add_f32_e32 v82, v82, v91
	v_mul_f32_e32 v91, v108, v167
	v_fma_f32 v92, v108, v167, v107
	v_mul_f32_e32 v108, v93, v172
	v_add_f32_e32 v82, v82, v92
	v_mul_f32_e32 v92, v109, v169
	v_fma_f32 v93, v109, v169, v108
	v_mul_f32_e32 v109, v94, v174
	v_add_f32_e32 v82, v82, v93
	v_mul_f32_e32 v93, v110, v171
	v_fma_f32 v94, v110, v171, v109
	v_mul_f32_e32 v110, v95, v176
	v_add_f32_e32 v82, v82, v94
	v_mul_f32_e32 v94, v111, v173
	v_fma_f32 v95, v111, v173, v110
	v_mul_f32_e32 v111, v96, v177
	v_add_f32_e32 v82, v82, v95
	v_fma_f32 v96, v112, v175, v111
	v_mul_f32_e32 v95, v112, v175
	v_add_f32_e32 v112, v82, v96
	v_mov_b32_e32 v96, v113
	v_pk_mul_f32 v[98:99], v[96:97], v[146:147]
	v_cvt_pk_bf16_f32 v82, v181, v151
	v_cvt_pk_bf16_f32 v83, v83, v84
	v_cvt_pk_bf16_f32 v84, v85, v86
	v_cvt_pk_bf16_f32 v85, v87, v88
	v_cvt_pk_bf16_f32 v86, v89, v90
	v_cvt_pk_bf16_f32 v87, v91, v92
	v_cvt_pk_bf16_f32 v88, v93, v94
	s_nop 0
	v_cvt_pk_bf16_f32 v89, v95, v98
	v_add_f32_e32 v98, v98, v99
	v_cvt_pk_bf16_f32 v90, v148, v152
	v_cvt_pk_bf16_f32 v91, v150, v100
	v_cvt_pk_bf16_f32 v92, v101, v102
	v_cvt_pk_bf16_f32 v93, v103, v104
	v_cvt_pk_bf16_f32 v94, v105, v106
	v_cvt_pk_bf16_f32 v95, v107, v108
	v_cvt_pk_bf16_f32 v96, v109, v110
	v_cvt_pk_bf16_f32 v97, v111, v99
	v_add_f32_e32 v180, v112, v98
	ds_read_b64_tr_b16 v[98:99], v203 offset:0x4000
	ds_read_b64_tr_b16 v[100:101], v203 offset:0x4800
	ds_read_b64_tr_b16 v[102:103], v203 offset:0x5000
	ds_read_b64_tr_b16 v[104:105], v203 offset:0x5800
	ds_read_b64_tr_b16 v[106:107], v203 offset:0x6000
	ds_read_b64_tr_b16 v[108:109], v203 offset:0x6800
	ds_read_b64_tr_b16 v[110:111], v203 offset:0x7000
	ds_read_b64_tr_b16 v[112:113], v203 offset:0x7800
	s_waitcnt lgkmcnt(0)
	v_permlane32_swap_b32_e32 v82, v84
	v_permlane32_swap_b32_e32 v83, v85
	v_permlane32_swap_b32_e32 v86, v88
	v_permlane32_swap_b32_e32 v87, v89
	v_permlane32_swap_b32_e32 v90, v92
	v_permlane32_swap_b32_e32 v91, v93
	v_permlane32_swap_b32_e32 v94, v96
	v_permlane32_swap_b32_e32 v95, v97
	v_mfma_f32_32x32x16_bf16 v[50:65], v[82:85], v[98:101], v[50:65]
	ds_read_b64_tr_b16 v[98:99], v203 offset:0x4200
	ds_read_b64_tr_b16 v[100:101], v203 offset:0x4a00
	v_mfma_f32_32x32x16_bf16 v[50:65], v[86:89], v[102:105], v[50:65]
	ds_read_b64_tr_b16 v[102:103], v203 offset:0x5200
	ds_read_b64_tr_b16 v[104:105], v203 offset:0x5a00
	v_mfma_f32_32x32x16_bf16 v[50:65], v[90:93], v[106:109], v[50:65]
	ds_read_b64_tr_b16 v[106:107], v203 offset:0x6200
	ds_read_b64_tr_b16 v[108:109], v203 offset:0x6a00
	v_mfma_f32_32x32x16_bf16 v[50:65], v[94:97], v[110:113], v[50:65]
	ds_read_b64_tr_b16 v[110:111], v203 offset:0x7200
	ds_read_b64_tr_b16 v[112:113], v203 offset:0x7a00
	s_waitcnt lgkmcnt(0)
	v_mfma_f32_32x32x16_bf16 v[66:81], v[82:85], v[98:101], v[66:81]
	v_mfma_f32_32x32x16_bf16 v[66:81], v[86:89], v[102:105], v[66:81]
	v_mfma_f32_32x32x16_bf16 v[66:81], v[90:93], v[106:109], v[66:81]
	v_mfma_f32_32x32x16_bf16 v[66:81], v[94:97], v[110:113], v[66:81]
